# P0: first x row and b_f of the rows loop loaded before the forget-weight LDS fill (round trip overlapped with the fill)
# baseline (speedup 1.0000x reference)
.LBB0_99:
	s_or_b64 exec, exec, s[8:9]
	v_lshrrev_b32_e32 v5, 9, v208
	v_sub_u32_e32 v2, 30, v5
	v_and_b32_e32 v1, 15, v208
	v_lshrrev_b32_e32 v2, 1, v2
	v_lshlrev_b32_e32 v4, 12, v1
	v_add_u32_e32 v7, 1, v2
	v_add_u32_e32 v209, 0x200, v208
	v_add_u32_e32 v6, 0, v4
	v_or_b32_e32 v0, 0xc00, v1
	v_and_b32_e32 v8, 28, v7
	s_mov_b64 s[6:7], 0
	s_movk_i32 s8, 0xc10
	v_mov_b32_e32 v9, 0
	v_mov_b64_e32 v[2:3], v[208:209]
	s_waitcnt lgkmcnt(0)
	s_cmpk_gt_i32 s36, 0x3fff
	s_cbranch_scc1 .Lrows_pf_skip
	s_mov_b32 s98, s36
	s_ashr_i32 s99, s36, 31
	s_lshl_b64 s[98:99], s[98:99], 12
	s_add_u32 s98, s20, s98
	s_addc_u32 s99, s21, s99
	v_lshlrev_b32_e32 v246, 4, v210
	v_mov_b32_e32 v247, 0
	v_lshl_add_u64 v[246:247], s[98:99], 0, v[246:247]
	global_load_dwordx4 v[120:123], v[246:247], off nt
	global_load_dwordx4 v[124:127], v[246:247], off offset:1024 nt
	global_load_dwordx4 v[144:147], v[246:247], off offset:2048 nt
	global_load_dwordx4 v[148:151], v[246:247], off offset:3072 nt
	v_and_b32_e32 v248, 60, v210
	v_mov_b32_e32 v249, 0
	v_lshl_add_u64 v[248:249], s[18:19], 0, v[248:249]
	global_load_dword v245, v[248:249], off
.Lrows_pf_skip:
	s_barrier
	v_lshrrev_b32_e32 v0, 2, v208
	v_and_b32_e32 v1, 3, v208
	v_mul_u32_u24_e32 v2, 0x3040, v0
	v_lshl_add_u32 v2, v1, 4, v2
	v_add_u32_e32 v2, 0x3000, v2
	v_mov_b32_e32 v3, 0
	v_lshl_add_u64 v[2:3], s[16:17], 0, v[2:3]
	v_lshlrev_b32_e32 v4, 14, v1
	v_lshl_add_u32 v4, v0, 2, v4
	s_mov_b64 s[8:9], 0
	v_lshl_add_u64 v[6:7], v[2:3], 0, s[8:9]
	global_load_dwordx4 v[10:13], v[6:7], off
	s_add_u32 s8, s8, 0x182000
	s_addc_u32 s9, s9, 0
	v_lshl_add_u64 v[6:7], v[2:3], 0, s[8:9]
	global_load_dwordx4 v[14:17], v[6:7], off
	s_add_u32 s8, s8, 0x182000
	s_addc_u32 s9, s9, 0
	v_lshl_add_u64 v[6:7], v[2:3], 0, s[8:9]
	global_load_dwordx4 v[18:21], v[6:7], off
	s_add_u32 s8, s8, 0x182000
	s_addc_u32 s9, s9, 0
	v_lshl_add_u64 v[6:7], v[2:3], 0, s[8:9]
	global_load_dwordx4 v[22:25], v[6:7], off
	s_add_u32 s8, s8, 0x182000
	s_addc_u32 s9, s9, 0
	v_lshl_add_u64 v[6:7], v[2:3], 0, s[8:9]
	global_load_dwordx4 v[26:29], v[6:7], off
	s_add_u32 s8, s8, 0x182000
	s_addc_u32 s9, s9, 0
	v_lshl_add_u64 v[6:7], v[2:3], 0, s[8:9]
	global_load_dwordx4 v[30:33], v[6:7], off
	s_add_u32 s8, s8, 0x182000
	s_addc_u32 s9, s9, 0
	v_lshl_add_u64 v[6:7], v[2:3], 0, s[8:9]
	global_load_dwordx4 v[34:37], v[6:7], off
	s_add_u32 s8, s8, 0x182000
	s_addc_u32 s9, s9, 0
	v_lshl_add_u64 v[6:7], v[2:3], 0, s[8:9]
	global_load_dwordx4 v[38:41], v[6:7], off
	s_waitcnt vmcnt(7)
	ds_write_b32 v4, v10
	ds_write_b32 v4, v11 offset:4096
	ds_write_b32 v4, v12 offset:8192
	ds_write_b32 v4, v13 offset:12288
	s_waitcnt vmcnt(6)
	ds_write_b32 v4, v14 offset:512
	ds_write_b32 v4, v15 offset:4608
	ds_write_b32 v4, v16 offset:8704
	ds_write_b32 v4, v17 offset:12800
	s_waitcnt vmcnt(5)
	ds_write_b32 v4, v18 offset:1024
	ds_write_b32 v4, v19 offset:5120
	ds_write_b32 v4, v20 offset:9216
	ds_write_b32 v4, v21 offset:13312
	s_waitcnt vmcnt(4)
	ds_write_b32 v4, v22 offset:1536
	ds_write_b32 v4, v23 offset:5632
	ds_write_b32 v4, v24 offset:9728
	ds_write_b32 v4, v25 offset:13824
	s_waitcnt vmcnt(3)
	ds_write_b32 v4, v26 offset:2048
	ds_write_b32 v4, v27 offset:6144
	ds_write_b32 v4, v28 offset:10240
	ds_write_b32 v4, v29 offset:14336
	s_waitcnt vmcnt(2)
	ds_write_b32 v4, v30 offset:2560
	ds_write_b32 v4, v31 offset:6656
	ds_write_b32 v4, v32 offset:10752
	ds_write_b32 v4, v33 offset:14848
	s_waitcnt vmcnt(1)
	ds_write_b32 v4, v34 offset:3072
	ds_write_b32 v4, v35 offset:7168
	ds_write_b32 v4, v36 offset:11264
	ds_write_b32 v4, v37 offset:15360
	s_waitcnt vmcnt(0)
	ds_write_b32 v4, v38 offset:3584
	ds_write_b32 v4, v39 offset:7680
	ds_write_b32 v4, v40 offset:11776
	ds_write_b32 v4, v41 offset:15872
	s_cmpk_gt_i32 s36, 0x3fff
	s_waitcnt lgkmcnt(0)
	s_barrier
	s_cbranch_scc1 .LBB0_114
	v_mbcnt_lo_u32_b32 v0, -1, 0
	v_mbcnt_hi_u32_b32 v0, -1, v0
	v_and_b32_e32 v1, 64, v0
	v_add_u32_e32 v1, 64, v1
	v_xor_b32_e32 v2, 1, v0
	v_cmp_lt_i32_e32 vcc, v2, v1
	s_add_u32 s42, s40, 0x100000
	v_mov_b32_e32 v213, 0
	v_cndmask_b32_e32 v2, v0, v2, vcc
	v_lshlrev_b32_e32 v209, 2, v2
	v_xor_b32_e32 v2, 2, v0
	v_cmp_lt_i32_e32 vcc, v2, v1
	s_addc_u32 s43, s41, 0
	s_ashr_i32 s37, s36, 31
	v_cndmask_b32_e32 v2, v0, v2, vcc
	v_lshlrev_b32_e32 v211, 2, v2
	v_xor_b32_e32 v2, 4, v0
	v_cmp_lt_i32_e32 vcc, v2, v1
	v_lshlrev_b32_e32 v212, 4, v210
	v_lshl_add_u64 v[214:215], s[22:23], 0, v[212:213]
	v_cndmask_b32_e32 v2, v0, v2, vcc
	v_lshlrev_b32_e32 v238, 2, v2
	v_xor_b32_e32 v2, 8, v0
	v_cmp_lt_i32_e32 vcc, v2, v1
	s_mov_b32 s45, 0
	v_cmp_eq_u32_e64 s[6:7], 0, v210
	v_cndmask_b32_e32 v2, v0, v2, vcc
	v_lshlrev_b32_e32 v239, 2, v2
	v_xor_b32_e32 v2, 16, v0
	v_cmp_lt_i32_e32 vcc, v2, v1
	v_add_u32_e32 v242, 0, v212
	v_cmp_gt_u32_e64 s[8:9], 32, v210
	v_cndmask_b32_e32 v2, v0, v2, vcc
	v_lshlrev_b32_e32 v240, 2, v2
	v_xor_b32_e32 v2, 32, v0
	v_cmp_lt_i32_e32 vcc, v2, v1
	v_mov_b32_e32 v1, v213
	v_lshrrev_b32_e32 v243, 2, v210
	v_cndmask_b32_e32 v0, v0, v2, vcc
	v_lshlrev_b32_e32 v241, 2, v0
	v_and_b32_e32 v0, 16, v208
	v_cmp_eq_u32_e64 s[10:11], 0, v0
	v_and_b32_e32 v0, 8, v208
	v_cmp_eq_u32_e64 s[12:13], 0, v0
	v_and_b32_e32 v0, 4, v208
	v_cmp_eq_u32_e64 s[14:15], 0, v0
	v_and_b32_e32 v0, 3, v208
	v_cmp_eq_u32_e64 s[16:17], 0, v0
	v_and_b32_e32 v0, 60, v210
	v_lshl_add_u64 v[216:217], s[18:19], 0, v[0:1]
	s_lshl_b64 s[18:19], s[36:37], 2
	s_add_u32 s48, s18, 0x30000
	s_addc_u32 s49, s19, 0
	s_ashr_i32 s39, s38, 31
	s_lshl_b64 s[18:19], s[36:37], 11
	s_lshl_b64 s[22:23], s[38:39], 2
	v_lshl_or_b32 v218, v210, 3, s18
	v_mov_b32_e32 v219, s19
	s_lshl_b64 s[46:47], s[38:39], 11
	s_lshl_b64 s[18:19], s[36:37], 12
	s_add_u32 s18, s20, s18
	s_addc_u32 s19, s21, s19
	v_lshl_add_u64 v[0:1], s[18:19], 0, v[212:213]
	s_mov_b64 s[18:19], 0x800
	v_lshl_add_u64 v[220:221], v[0:1], 0, s[18:19]
	s_lshl_b64 s[20:21], s[38:39], 12
	v_mov_b32_e32 v212, 0x358637bd
	s_mov_b32 s37, 0xf800000
	v_mov_b32_e32 v244, 0x260
	s_mov_b32 s39, 0x4600000
	s_mov_b32 s50, 0xbfb8aa3b
	s_branch .LBB0_110
